# type-C attention fast loop rewritten as anti-phase ping-pong: waves 0-3 / 4-7 one segment apart, pure-MFMA segment (QK(t)+PV(t-1)) vs pure-VALU segment (exp/cvt/rowsum, LDS staging), 4 LDS stages
# speedup vs baseline: 1.0382x; 1.0162x over previous
.LBB0_159:
	s_or_b64 exec, exec, s[14:15]
	global_load_dwordx4 v[124:127], v[10:11], off offset:128
	s_movk_i32 s6, 0xd0
	v_mul_lo_u32 v9, v12, s6
	v_lshl_add_u32 v157, v6, 4, v9
	v_mul_lo_u32 v6, v7, s6
	v_lshl_add_u32 v158, v8, 4, v6
	s_waitcnt vmcnt(3)
	ds_write_b128 v157, v[104:107]
	s_and_saveexec_b64 s[12:13], s[38:39]
	ds_write_b128 v158, v[112:115]
	s_or_b64 exec, exec, s[12:13]
	v_mad_i64_i32 v[6:7], s[12:13], v156, s54, 0
	s_and_b64 s[12:13], s[88:89], exec
	s_cselect_b32 s14, 0x84, 4
	v_lshl_add_u64 v[6:7], s[2:3], 0, v[6:7]
	s_add_u32 s2, s52, s96
	v_lshl_add_u64 v[6:7], v[6:7], 0, v[0:1]
	s_addc_u32 s3, s53, 0
	v_lshl_add_u64 v[150:151], s[2:3], 0, v[6:7]
	s_add_u32 s2, s40, s41
	v_and_b32_e32 v8, 31, v148
	s_addc_u32 s3, s23, 0
	v_mul_u32_u24_e32 v16, 0xd0, v8
	v_lshlrev_b32_e32 v8, 6, v8
	v_cmp_lt_i32_e32 vcc, v207, v206
	s_add_u32 s2, s52, s2
	v_mul_lo_u32 v9, v156, s4
	v_sub_u32_e32 v17, v16, v8
	v_cndmask_b32_e32 v8, v205, v207, vcc
	s_addc_u32 s3, s53, s3
	v_mov_b32_e32 v14, v1
	v_mov_b32_e32 v15, v1
	v_lshl_add_u32 v160, v140, 4, v9
	v_lshlrev_b32_e32 v159, 2, v8
	v_lshl_add_u64 v[152:153], v[2:3], 1, s[2:3]
	v_lshl_add_u64 v[154:155], v[4:5], 1, s[2:3]
	v_mov_b32_e32 v0, v1
	v_mov_b32_e32 v2, v1
	v_mov_b32_e32 v3, v1
	v_mov_b32_e32 v4, v1
	v_mov_b32_e32 v5, v1
	v_mov_b32_e32 v6, v1
	v_mov_b32_e32 v7, v1
	v_mov_b32_e32 v8, v1
	v_mov_b32_e32 v9, v1
	v_mov_b32_e32 v10, v1
	v_mov_b32_e32 v11, v1
	v_mov_b32_e32 v12, v1
	v_mov_b32_e32 v13, v1
	v_add_u32_e32 v164, v16, v130
	v_add_u32_e32 v165, v17, v130
	v_mov_b64_e32 v[30:31], v[14:15]
	v_mov_b64_e32 v[46:47], v[14:15]
	s_mov_b32 s22, 0
	v_mov_b32_e32 v161, 0
	v_bfrev_b32_e32 v218, 1
	v_mov_b32_e32 v219, v218
	v_mov_b32_e32 v220, v218
	v_mov_b32_e32 v221, v218
	v_mov_b32_e32 v222, v218
	v_mov_b32_e32 v223, v218
	v_mov_b32_e32 v224, v218
	v_mov_b32_e32 v225, v218
	v_mov_b32_e32 v226, v218
	v_mov_b32_e32 v227, v218
	v_mov_b32_e32 v228, v218
	v_mov_b32_e32 v229, v218
	v_mov_b32_e32 v230, v218
	v_mov_b32_e32 v231, v218
	v_mov_b32_e32 v232, v218
	v_mov_b32_e32 v233, v218
	v_mov_b64_e32 v[28:29], v[12:13]
	v_mov_b64_e32 v[26:27], v[10:11]
	v_mov_b64_e32 v[24:25], v[8:9]
	v_mov_b64_e32 v[22:23], v[6:7]
	v_mov_b64_e32 v[20:21], v[4:5]
	v_mov_b64_e32 v[18:19], v[2:3]
	v_mov_b64_e32 v[16:17], v[0:1]
	v_mov_b64_e32 v[44:45], v[12:13]
	v_mov_b64_e32 v[42:43], v[10:11]
	v_mov_b64_e32 v[40:41], v[8:9]
	v_mov_b64_e32 v[38:39], v[6:7]
	v_mov_b64_e32 v[36:37], v[4:5]
	v_mov_b64_e32 v[34:35], v[2:3]
	v_mov_b64_e32 v[32:33], v[0:1]
	v_mov_b32_e32 v0, 0
	s_waitcnt vmcnt(2)
	ds_write_b128 v160, v[120:123] offset:13312
	s_waitcnt lgkmcnt(0)
	s_barrier
	s_cmp_lg_u32 s98, 0
	s_cbranch_scc1 .LBB0_162_sl
	v_lshl_add_u64 v[236:237], v[152:153], 0, s[20:21]
	v_lshl_add_u64 v[240:241], v[154:155], 0, s[20:21]
	v_lshl_add_u64 v[244:245], v[150:151], 0, s[20:21]
	s_mov_b32 s2, 0x9186800
	s_mov_b32 s3, 0
	v_lshl_add_u64 v[238:239], v[236:237], 0, s[2:3]
	v_lshl_add_u64 v[242:243], v[240:241], 0, s[2:3]
	s_mov_b32 s2, 0x9183800
	v_lshl_add_u64 v[236:237], v[236:237], 0, s[2:3]
	v_lshl_add_u64 v[240:241], v[240:241], 0, s[2:3]
	s_mov_b32 s2, 0xa40d900
	v_lshl_add_u64 v[244:245], v[244:245], 0, s[2:3]
	s_cmp_eq_u64 s[38:39], 0
	s_cselect_b32 s13, 1, 0
	v_add_u32_e32 v246, 0xb000, v157
	v_add_u32_e32 v247, 0xb000, v158
	v_add_u32_e32 v248, 0xb000, v160
	v_add_u32_e32 v249, 0xb000, v164
	v_add_u32_e32 v250, 0xb000, v165
	s_waitcnt vmcnt(0)
	ds_write_b128 v157, v[116:119] offset:22528
	s_and_saveexec_b64 s[2:3], s[38:39]
	ds_write_b128 v158, v[108:111] offset:22528
	s_or_b64 exec, exec, s[2:3]
	ds_write_b128 v160, v[124:127] offset:35840
	s_cmp_lg_u32 s13, 0
	s_cbranch_scc1 .Lppc_l2_1
	global_load_dwordx4 v[104:107], v[236:237], off
	global_load_dwordx4 v[112:115], v[240:241], off
	global_load_dwordx4 v[120:123], v[244:245], off
	s_branch .Lppc_lj_1
.Lppc_l2_1:
	global_load_dwordx4 v[104:107], v[236:237], off
	global_load_dwordx4 v[120:123], v[244:245], off
.Lppc_lj_1:
	s_cmp_lg_u32 s13, 0
	s_cbranch_scc1 .Lppc_l2_2
	global_load_dwordx4 v[116:119], v[238:239], off
	global_load_dwordx4 v[108:111], v[242:243], off
	global_load_dwordx4 v[124:127], v[244:245], off offset:128
	s_branch .Lppc_lj_2
.Lppc_l2_2:
	global_load_dwordx4 v[116:119], v[238:239], off
	global_load_dwordx4 v[124:127], v[244:245], off offset:128
.Lppc_lj_2:
	v_lshl_add_u64 v[244:245], v[244:245], 0, s[30:31]
	v_lshl_add_u64 v[236:237], v[236:237], 0, s[26:27]
	v_lshl_add_u64 v[238:239], v[238:239], 0, s[26:27]
	v_lshl_add_u64 v[240:241], v[240:241], 0, s[26:27]
	v_lshl_add_u64 v[242:243], v[242:243], 0, s[26:27]
	s_waitcnt lgkmcnt(0)
	s_barrier
	s_cmp_lg_u32 s13, 0
	s_cbranch_scc0 .Lppc_nolag
	s_barrier
.Lppc_nolag:
	ds_read_b128 v[2:5], v164
	ds_read_b128 v[6:9], v164 offset:32
	ds_read_b128 v[10:13], v164 offset:6656
	ds_read_b128 v[128:131], v164 offset:6688
	ds_read_b128 v[132:135], v164 offset:64
	ds_read_b128 v[136:139], v164 offset:96
	ds_read_b128 v[140:143], v164 offset:6720
	ds_read_b128 v[144:147], v164 offset:6752
	ds_read_b128 v[166:169], v164 offset:128
	ds_read_b128 v[170:173], v164 offset:160
	ds_read_b128 v[174:177], v164 offset:6784
	ds_read_b128 v[178:181], v164 offset:6816
	s_waitcnt lgkmcnt(11)
	s_nop 0
	v_mfma_f32_32x32x16_bf16 v[64:79], v[2:5], v[80:83], v[218:233]
	s_waitcnt lgkmcnt(9)
	v_mfma_f32_32x32x16_bf16 v[48:63], v[10:13], v[80:83], v[218:233]
	v_mfma_f32_32x32x16_bf16 v[64:79], v[6:9], v[84:87], v[64:79]
	s_waitcnt lgkmcnt(8)
	v_mfma_f32_32x32x16_bf16 v[48:63], v[128:131], v[84:87], v[48:63]
	s_waitcnt lgkmcnt(7)
	v_mfma_f32_32x32x16_bf16 v[64:79], v[132:135], v[88:91], v[64:79]
	s_waitcnt lgkmcnt(5)
	v_mfma_f32_32x32x16_bf16 v[48:63], v[140:143], v[88:91], v[48:63]
	v_mfma_f32_32x32x16_bf16 v[64:79], v[136:139], v[92:95], v[64:79]
	s_waitcnt lgkmcnt(4)
	v_mfma_f32_32x32x16_bf16 v[48:63], v[144:147], v[92:95], v[48:63]
	s_waitcnt lgkmcnt(3)
	v_mfma_f32_32x32x16_bf16 v[64:79], v[166:169], v[96:99], v[64:79]
	s_waitcnt lgkmcnt(1)
	v_mfma_f32_32x32x16_bf16 v[48:63], v[174:177], v[96:99], v[48:63]
	v_mfma_f32_32x32x16_bf16 v[64:79], v[170:173], v[100:103], v[64:79]
	s_waitcnt lgkmcnt(0)
	v_mfma_f32_32x32x16_bf16 v[48:63], v[178:181], v[100:103], v[48:63]
	s_nop 15
	s_barrier
	v_max3_f32 v166, v64, v65, v66
	v_max3_f32 v167, v48, v49, v50
	v_max3_f32 v166, v166, v67, v68
	v_max3_f32 v166, v166, v69, v70
	v_max3_f32 v166, v166, v71, v72
	v_max3_f32 v166, v166, v73, v74
	v_max3_f32 v166, v166, v75, v76
	v_max3_f32 v166, v166, v77, v78
	v_max3_f32 v167, v167, v51, v52
	v_max3_f32 v167, v167, v53, v54
	v_max3_f32 v167, v167, v55, v56
	v_max3_f32 v167, v167, v57, v58
	v_max3_f32 v167, v167, v59, v60
	v_max3_f32 v167, v167, v61, v62
	v_max3_f32 v166, v166, v79, v63
	v_max_f32_e32 v166, v166, v167
	ds_bpermute_b32 v167, v159, v166
	s_waitcnt lgkmcnt(0)
	v_max_f32_e32 v166, v166, v167
	v_add_f32_e32 v161, v161, v166
	v_xor_b32_e32 v218, 0x80000000, v166
	v_mov_b32_e32 v219, v218
	v_mov_b32_e32 v220, v218
	v_mov_b32_e32 v221, v218
	v_mov_b32_e32 v222, v218
	v_mov_b32_e32 v223, v218
	v_mov_b32_e32 v224, v218
	v_mov_b32_e32 v225, v218
	v_mov_b32_e32 v226, v218
	v_mov_b32_e32 v227, v218
	v_mov_b32_e32 v228, v218
	v_mov_b32_e32 v229, v218
	v_mov_b32_e32 v230, v218
	v_mov_b32_e32 v231, v218
	v_mov_b32_e32 v232, v218
	v_mov_b32_e32 v233, v218
	v_sub_f32_e32 v64, v64, v166
	v_sub_f32_e32 v65, v65, v166
	v_sub_f32_e32 v66, v66, v166
	v_sub_f32_e32 v67, v67, v166
	v_sub_f32_e32 v68, v68, v166
	v_sub_f32_e32 v69, v69, v166
	v_sub_f32_e32 v70, v70, v166
	v_sub_f32_e32 v71, v71, v166
	v_sub_f32_e32 v72, v72, v166
	v_sub_f32_e32 v73, v73, v166
	v_sub_f32_e32 v74, v74, v166
	v_sub_f32_e32 v75, v75, v166
	v_sub_f32_e32 v76, v76, v166
	v_sub_f32_e32 v77, v77, v166
	v_sub_f32_e32 v78, v78, v166
	v_sub_f32_e32 v79, v79, v166
	v_sub_f32_e32 v48, v48, v166
	v_sub_f32_e32 v49, v49, v166
	v_sub_f32_e32 v50, v50, v166
	v_sub_f32_e32 v51, v51, v166
	v_sub_f32_e32 v52, v52, v166
	v_sub_f32_e32 v53, v53, v166
	v_sub_f32_e32 v54, v54, v166
	v_sub_f32_e32 v55, v55, v166
	v_sub_f32_e32 v56, v56, v166
	v_sub_f32_e32 v57, v57, v166
	v_sub_f32_e32 v58, v58, v166
	v_sub_f32_e32 v59, v59, v166
	v_sub_f32_e32 v60, v60, v166
	v_sub_f32_e32 v61, v61, v166
	v_sub_f32_e32 v62, v62, v166
	v_sub_f32_e32 v63, v63, v166
	v_exp_f32_e32 v64, v64
	v_exp_f32_e32 v65, v65
	v_exp_f32_e32 v66, v66
	v_exp_f32_e32 v67, v67
	v_exp_f32_e32 v68, v68
	v_exp_f32_e32 v69, v69
	v_exp_f32_e32 v70, v70
	v_exp_f32_e32 v71, v71
	v_cvt_pk_bf16_f32 v188, v64, v65
	v_cvt_pk_bf16_f32 v189, v66, v67
	v_cvt_pk_bf16_f32 v190, v68, v69
	v_cvt_pk_bf16_f32 v191, v70, v71
	v_exp_f32_e32 v72, v72
	v_exp_f32_e32 v73, v73
	v_exp_f32_e32 v74, v74
	v_exp_f32_e32 v75, v75
	v_exp_f32_e32 v76, v76
	v_exp_f32_e32 v77, v77
	v_exp_f32_e32 v78, v78
	v_exp_f32_e32 v79, v79
	v_cvt_pk_bf16_f32 v192, v72, v73
	v_cvt_pk_bf16_f32 v193, v74, v75
	v_cvt_pk_bf16_f32 v194, v76, v77
	v_cvt_pk_bf16_f32 v195, v78, v79
	s_cmp_lg_u32 s13, 0
	s_cbranch_scc1 .Lppc_w2_3
	s_waitcnt vmcnt(3)
	ds_write_b128 v157, v[104:107] offset:45056
	ds_write_b128 v158, v[112:115] offset:45056
	ds_write_b128 v160, v[120:123] offset:58368
	global_load_dwordx4 v[104:107], v[236:237], off
	global_load_dwordx4 v[112:115], v[240:241], off
	global_load_dwordx4 v[120:123], v[244:245], off
	s_branch .Lppc_wj_3
.Lppc_w2_3:
	s_waitcnt vmcnt(2)
	ds_write_b128 v157, v[104:107] offset:45056
	ds_write_b128 v160, v[120:123] offset:58368
	global_load_dwordx4 v[104:107], v[236:237], off
	global_load_dwordx4 v[120:123], v[244:245], off
.Lppc_wj_3:
	v_exp_f32_e32 v48, v48
	v_exp_f32_e32 v49, v49
	v_exp_f32_e32 v50, v50
	v_exp_f32_e32 v51, v51
	v_exp_f32_e32 v52, v52
	v_exp_f32_e32 v53, v53
	v_exp_f32_e32 v54, v54
	v_exp_f32_e32 v55, v55
	v_cvt_pk_bf16_f32 v196, v48, v49
	v_cvt_pk_bf16_f32 v197, v50, v51
	v_cvt_pk_bf16_f32 v198, v52, v53
	v_cvt_pk_bf16_f32 v199, v54, v55
	v_exp_f32_e32 v56, v56
	v_exp_f32_e32 v57, v57
	v_exp_f32_e32 v58, v58
	v_exp_f32_e32 v59, v59
	v_exp_f32_e32 v60, v60
	v_exp_f32_e32 v61, v61
	v_exp_f32_e32 v62, v62
	v_exp_f32_e32 v63, v63
	v_cvt_pk_bf16_f32 v208, v56, v57
	v_cvt_pk_bf16_f32 v209, v58, v59
	v_cvt_pk_bf16_f32 v210, v60, v61
	v_cvt_pk_bf16_f32 v211, v62, v63
	ds_read_b128 v[2:5], v164 offset:22528
	ds_read_b128 v[6:9], v164 offset:22560
	ds_read_b128 v[10:13], v164 offset:29184
	ds_read_b128 v[128:131], v164 offset:29216
	v_add_f32_e32 v14, v64, v65
	v_add_f32_e32 v15, v48, v49
	v_add_f32_e32 v14, v66, v14
	v_add_f32_e32 v15, v50, v15
	v_add_f32_e32 v14, v67, v14
	v_add_f32_e32 v15, v51, v15
	v_add_f32_e32 v14, v68, v14
	v_add_f32_e32 v15, v52, v15
	v_add_f32_e32 v14, v69, v14
	v_add_f32_e32 v15, v53, v15
	v_add_f32_e32 v14, v70, v14
	v_add_f32_e32 v15, v54, v15
	v_add_f32_e32 v14, v71, v14
	v_add_f32_e32 v15, v55, v15
	v_add_f32_e32 v14, v72, v14
	v_add_f32_e32 v15, v56, v15
	v_add_f32_e32 v14, v73, v14
	v_add_f32_e32 v15, v57, v15
	v_add_f32_e32 v14, v74, v14
	v_add_f32_e32 v15, v58, v15
	v_add_f32_e32 v14, v75, v14
	v_add_f32_e32 v15, v59, v15
	v_add_f32_e32 v14, v76, v14
	v_add_f32_e32 v15, v60, v15
	v_add_f32_e32 v14, v77, v14
	v_add_f32_e32 v15, v61, v15
	v_add_f32_e32 v14, v78, v14
	v_add_f32_e32 v15, v62, v15
	v_add_f32_e32 v14, v79, v14
	v_add_f32_e32 v15, v63, v15
	v_add_f32_e32 v14, v15, v14
	v_add_f32_e32 v0, v0, v14
	s_waitcnt lgkmcnt(0)
	s_barrier
	s_mov_b32 s22, 0
.Lppc_loop:
	ds_read_b128 v[132:135], v164 offset:22592
	ds_read_b128 v[136:139], v164 offset:22624
	ds_read_b128 v[140:143], v164 offset:29248
	ds_read_b128 v[144:147], v164 offset:29280
	ds_read_b128 v[166:169], v164 offset:22656
	ds_read_b128 v[170:173], v164 offset:22688
	ds_read_b128 v[174:177], v164 offset:29312
	ds_read_b128 v[178:181], v164 offset:29344
	v_mfma_f32_32x32x16_bf16 v[64:79], v[2:5], v[80:83], v[218:233]
	v_mfma_f32_32x32x16_bf16 v[48:63], v[10:13], v[80:83], v[218:233]
	v_mfma_f32_32x32x16_bf16 v[64:79], v[6:9], v[84:87], v[64:79]
	v_mfma_f32_32x32x16_bf16 v[48:63], v[128:131], v[84:87], v[48:63]
	ds_read_b128 v[128:131], v165 offset:17920
	ds_read_b128 v[10:13], v165 offset:17952
	ds_read_b128 v[2:5], v165 offset:17984
	ds_read_b128 v[6:9], v165 offset:18016
	s_waitcnt lgkmcnt(11)
	v_mfma_f32_32x32x16_bf16 v[64:79], v[132:135], v[88:91], v[64:79]
	s_waitcnt lgkmcnt(9)
	v_mfma_f32_32x32x16_bf16 v[48:63], v[140:143], v[88:91], v[48:63]
	v_mfma_f32_32x32x16_bf16 v[64:79], v[136:139], v[92:95], v[64:79]
	s_waitcnt lgkmcnt(8)
	v_mfma_f32_32x32x16_bf16 v[48:63], v[144:147], v[92:95], v[48:63]
	ds_read_b128 v[144:147], v165 offset:13312
	ds_read_b128 v[140:143], v165 offset:13344
	ds_read_b128 v[136:139], v165 offset:13376
	ds_read_b128 v[132:135], v165 offset:13408
	s_waitcnt lgkmcnt(11)
	v_mfma_f32_32x32x16_bf16 v[64:79], v[166:169], v[96:99], v[64:79]
	s_waitcnt lgkmcnt(9)
	v_mfma_f32_32x32x16_bf16 v[48:63], v[174:177], v[96:99], v[48:63]
	v_mfma_f32_32x32x16_bf16 v[64:79], v[170:173], v[100:103], v[64:79]
	s_waitcnt lgkmcnt(8)
	v_mfma_f32_32x32x16_bf16 v[48:63], v[178:181], v[100:103], v[48:63]
	s_waitcnt lgkmcnt(3)
	v_mfma_f32_32x32x16_bf16 v[32:47], v[144:147], v[188:191], v[32:47]
	v_mfma_f32_32x32x16_bf16 v[16:31], v[128:131], v[188:191], v[16:31]
	s_waitcnt lgkmcnt(2)
	v_mfma_f32_32x32x16_bf16 v[32:47], v[140:143], v[192:195], v[32:47]
	v_mfma_f32_32x32x16_bf16 v[16:31], v[10:13], v[192:195], v[16:31]
	s_waitcnt lgkmcnt(1)
	v_mfma_f32_32x32x16_bf16 v[32:47], v[136:139], v[196:199], v[32:47]
	v_mfma_f32_32x32x16_bf16 v[16:31], v[2:5], v[196:199], v[16:31]
	s_waitcnt lgkmcnt(0)
	v_mfma_f32_32x32x16_bf16 v[32:47], v[132:135], v[208:211], v[32:47]
	v_mfma_f32_32x32x16_bf16 v[16:31], v[6:9], v[208:211], v[16:31]
	s_barrier
	v_exp_f32_e32 v64, v64
	v_exp_f32_e32 v65, v65
	v_exp_f32_e32 v66, v66
	v_exp_f32_e32 v67, v67
	v_exp_f32_e32 v68, v68
	v_exp_f32_e32 v69, v69
	v_exp_f32_e32 v70, v70
	v_exp_f32_e32 v71, v71
	v_cvt_pk_bf16_f32 v188, v64, v65
	v_cvt_pk_bf16_f32 v189, v66, v67
	v_cvt_pk_bf16_f32 v190, v68, v69
	v_cvt_pk_bf16_f32 v191, v70, v71
	v_exp_f32_e32 v72, v72
	v_exp_f32_e32 v73, v73
	v_exp_f32_e32 v74, v74
	v_exp_f32_e32 v75, v75
	v_exp_f32_e32 v76, v76
	v_exp_f32_e32 v77, v77
	v_exp_f32_e32 v78, v78
	v_exp_f32_e32 v79, v79
	v_cvt_pk_bf16_f32 v192, v72, v73
	v_cvt_pk_bf16_f32 v193, v74, v75
	v_cvt_pk_bf16_f32 v194, v76, v77
	v_cvt_pk_bf16_f32 v195, v78, v79
	s_cmp_lg_u32 s13, 0
	s_cbranch_scc1 .Lppc_w2_4
	s_waitcnt vmcnt(3)
	ds_write_b128 v246, v[116:119] offset:22528
	ds_write_b128 v247, v[108:111] offset:22528
	ds_write_b128 v248, v[124:127] offset:35840
	global_load_dwordx4 v[116:119], v[238:239], off
	global_load_dwordx4 v[108:111], v[242:243], off
	global_load_dwordx4 v[124:127], v[244:245], off offset:128
	s_branch .Lppc_wj_4
.Lppc_w2_4:
	s_waitcnt vmcnt(2)
	ds_write_b128 v246, v[116:119] offset:22528
	ds_write_b128 v248, v[124:127] offset:35840
	global_load_dwordx4 v[116:119], v[238:239], off
	global_load_dwordx4 v[124:127], v[244:245], off offset:128
.Lppc_wj_4:
	v_exp_f32_e32 v48, v48
	v_exp_f32_e32 v49, v49
	v_exp_f32_e32 v50, v50
	v_exp_f32_e32 v51, v51
	v_exp_f32_e32 v52, v52
	v_exp_f32_e32 v53, v53
	v_exp_f32_e32 v54, v54
	v_exp_f32_e32 v55, v55
	v_cvt_pk_bf16_f32 v196, v48, v49
	v_cvt_pk_bf16_f32 v197, v50, v51
	v_cvt_pk_bf16_f32 v198, v52, v53
	v_cvt_pk_bf16_f32 v199, v54, v55
	v_exp_f32_e32 v56, v56
	v_exp_f32_e32 v57, v57
	v_exp_f32_e32 v58, v58
	v_exp_f32_e32 v59, v59
	v_exp_f32_e32 v60, v60
	v_exp_f32_e32 v61, v61
	v_exp_f32_e32 v62, v62
	v_exp_f32_e32 v63, v63
	v_cvt_pk_bf16_f32 v208, v56, v57
	v_cvt_pk_bf16_f32 v209, v58, v59
	v_cvt_pk_bf16_f32 v210, v60, v61
	v_cvt_pk_bf16_f32 v211, v62, v63
	ds_read_b128 v[2:5], v164 offset:45056
	ds_read_b128 v[6:9], v164 offset:45088
	ds_read_b128 v[10:13], v164 offset:51712
	ds_read_b128 v[128:131], v164 offset:51744
	v_add_f32_e32 v14, v64, v65
	v_add_f32_e32 v15, v48, v49
	v_add_f32_e32 v14, v66, v14
	v_add_f32_e32 v15, v50, v15
	v_add_f32_e32 v14, v67, v14
	v_add_f32_e32 v15, v51, v15
	v_add_f32_e32 v14, v68, v14
	v_add_f32_e32 v15, v52, v15
	v_add_f32_e32 v14, v69, v14
	v_add_f32_e32 v15, v53, v15
	v_add_f32_e32 v14, v70, v14
	v_add_f32_e32 v15, v54, v15
	v_add_f32_e32 v14, v71, v14
	v_add_f32_e32 v15, v55, v15
	v_add_f32_e32 v14, v72, v14
	v_add_f32_e32 v15, v56, v15
	v_add_f32_e32 v14, v73, v14
	v_add_f32_e32 v15, v57, v15
	v_add_f32_e32 v14, v74, v14
	v_add_f32_e32 v15, v58, v15
	v_add_f32_e32 v14, v75, v14
	v_add_f32_e32 v15, v59, v15
	v_add_f32_e32 v14, v76, v14
	v_add_f32_e32 v15, v60, v15
	v_add_f32_e32 v14, v77, v14
	v_add_f32_e32 v15, v61, v15
	v_add_f32_e32 v14, v78, v14
	v_add_f32_e32 v15, v62, v15
	v_add_f32_e32 v14, v79, v14
	v_add_f32_e32 v15, v63, v15
	v_add_f32_e32 v14, v15, v14
	v_add_f32_e32 v0, v0, v14
	v_lshl_add_u64 v[244:245], v[244:245], 0, s[30:31]
	v_lshl_add_u64 v[236:237], v[236:237], 0, s[26:27]
	v_lshl_add_u64 v[238:239], v[238:239], 0, s[26:27]
	v_lshl_add_u64 v[240:241], v[240:241], 0, s[26:27]
	v_lshl_add_u64 v[242:243], v[242:243], 0, s[26:27]
	s_waitcnt lgkmcnt(0)
	s_barrier
	ds_read_b128 v[132:135], v164 offset:45120
	ds_read_b128 v[136:139], v164 offset:45152
	ds_read_b128 v[140:143], v164 offset:51776
	ds_read_b128 v[144:147], v164 offset:51808
	ds_read_b128 v[166:169], v164 offset:45184
	ds_read_b128 v[170:173], v164 offset:45216
	ds_read_b128 v[174:177], v164 offset:51840
	ds_read_b128 v[178:181], v164 offset:51872
	v_mfma_f32_32x32x16_bf16 v[64:79], v[2:5], v[80:83], v[218:233]
	v_mfma_f32_32x32x16_bf16 v[48:63], v[10:13], v[80:83], v[218:233]
	v_mfma_f32_32x32x16_bf16 v[64:79], v[6:9], v[84:87], v[64:79]
	v_mfma_f32_32x32x16_bf16 v[48:63], v[128:131], v[84:87], v[48:63]
	ds_read_b128 v[128:131], v165 offset:40448
	ds_read_b128 v[10:13], v165 offset:40480
	ds_read_b128 v[2:5], v165 offset:40512
	ds_read_b128 v[6:9], v165 offset:40544
	s_waitcnt lgkmcnt(11)
	v_mfma_f32_32x32x16_bf16 v[64:79], v[132:135], v[88:91], v[64:79]
	s_waitcnt lgkmcnt(9)
	v_mfma_f32_32x32x16_bf16 v[48:63], v[140:143], v[88:91], v[48:63]
	v_mfma_f32_32x32x16_bf16 v[64:79], v[136:139], v[92:95], v[64:79]
	s_waitcnt lgkmcnt(8)
	v_mfma_f32_32x32x16_bf16 v[48:63], v[144:147], v[92:95], v[48:63]
	ds_read_b128 v[144:147], v165 offset:35840
	ds_read_b128 v[140:143], v165 offset:35872
	ds_read_b128 v[136:139], v165 offset:35904
	ds_read_b128 v[132:135], v165 offset:35936
	s_waitcnt lgkmcnt(11)
	v_mfma_f32_32x32x16_bf16 v[64:79], v[166:169], v[96:99], v[64:79]
	s_waitcnt lgkmcnt(9)
	v_mfma_f32_32x32x16_bf16 v[48:63], v[174:177], v[96:99], v[48:63]
	v_mfma_f32_32x32x16_bf16 v[64:79], v[170:173], v[100:103], v[64:79]
	s_waitcnt lgkmcnt(8)
	v_mfma_f32_32x32x16_bf16 v[48:63], v[178:181], v[100:103], v[48:63]
	s_waitcnt lgkmcnt(3)
	v_mfma_f32_32x32x16_bf16 v[32:47], v[144:147], v[188:191], v[32:47]
	v_mfma_f32_32x32x16_bf16 v[16:31], v[128:131], v[188:191], v[16:31]
	s_waitcnt lgkmcnt(2)
	v_mfma_f32_32x32x16_bf16 v[32:47], v[140:143], v[192:195], v[32:47]
	v_mfma_f32_32x32x16_bf16 v[16:31], v[10:13], v[192:195], v[16:31]
	s_waitcnt lgkmcnt(1)
	v_mfma_f32_32x32x16_bf16 v[32:47], v[136:139], v[196:199], v[32:47]
	v_mfma_f32_32x32x16_bf16 v[16:31], v[2:5], v[196:199], v[16:31]
	s_waitcnt lgkmcnt(0)
	v_mfma_f32_32x32x16_bf16 v[32:47], v[132:135], v[208:211], v[32:47]
	v_mfma_f32_32x32x16_bf16 v[16:31], v[6:9], v[208:211], v[16:31]
	s_barrier
	v_exp_f32_e32 v64, v64
	v_exp_f32_e32 v65, v65
	v_exp_f32_e32 v66, v66
	v_exp_f32_e32 v67, v67
	v_exp_f32_e32 v68, v68
	v_exp_f32_e32 v69, v69
	v_exp_f32_e32 v70, v70
	v_exp_f32_e32 v71, v71
	v_cvt_pk_bf16_f32 v188, v64, v65
	v_cvt_pk_bf16_f32 v189, v66, v67
	v_cvt_pk_bf16_f32 v190, v68, v69
	v_cvt_pk_bf16_f32 v191, v70, v71
	v_exp_f32_e32 v72, v72
	v_exp_f32_e32 v73, v73
	v_exp_f32_e32 v74, v74
	v_exp_f32_e32 v75, v75
	v_exp_f32_e32 v76, v76
	v_exp_f32_e32 v77, v77
	v_exp_f32_e32 v78, v78
	v_exp_f32_e32 v79, v79
	v_cvt_pk_bf16_f32 v192, v72, v73
	v_cvt_pk_bf16_f32 v193, v74, v75
	v_cvt_pk_bf16_f32 v194, v76, v77
	v_cvt_pk_bf16_f32 v195, v78, v79
	s_cmp_lg_u32 s13, 0
	s_cbranch_scc1 .Lppc_w2_5
	s_waitcnt vmcnt(3)
	ds_write_b128 v157, v[104:107]
	ds_write_b128 v158, v[112:115]
	ds_write_b128 v160, v[120:123] offset:13312
	global_load_dwordx4 v[104:107], v[236:237], off
	global_load_dwordx4 v[112:115], v[240:241], off
	global_load_dwordx4 v[120:123], v[244:245], off
	s_branch .Lppc_wj_5
.Lppc_w2_5:
	s_waitcnt vmcnt(2)
	ds_write_b128 v157, v[104:107]
	ds_write_b128 v160, v[120:123] offset:13312
	global_load_dwordx4 v[104:107], v[236:237], off
	global_load_dwordx4 v[120:123], v[244:245], off
.Lppc_wj_5:
	v_exp_f32_e32 v48, v48
	v_exp_f32_e32 v49, v49
	v_exp_f32_e32 v50, v50
	v_exp_f32_e32 v51, v51
	v_exp_f32_e32 v52, v52
	v_exp_f32_e32 v53, v53
	v_exp_f32_e32 v54, v54
	v_exp_f32_e32 v55, v55
	v_cvt_pk_bf16_f32 v196, v48, v49
	v_cvt_pk_bf16_f32 v197, v50, v51
	v_cvt_pk_bf16_f32 v198, v52, v53
	v_cvt_pk_bf16_f32 v199, v54, v55
	v_exp_f32_e32 v56, v56
	v_exp_f32_e32 v57, v57
	v_exp_f32_e32 v58, v58
	v_exp_f32_e32 v59, v59
	v_exp_f32_e32 v60, v60
	v_exp_f32_e32 v61, v61
	v_exp_f32_e32 v62, v62
	v_exp_f32_e32 v63, v63
	v_cvt_pk_bf16_f32 v208, v56, v57
	v_cvt_pk_bf16_f32 v209, v58, v59
	v_cvt_pk_bf16_f32 v210, v60, v61
	v_cvt_pk_bf16_f32 v211, v62, v63
	ds_read_b128 v[2:5], v249 offset:22528
	ds_read_b128 v[6:9], v249 offset:22560
	ds_read_b128 v[10:13], v249 offset:29184
	ds_read_b128 v[128:131], v249 offset:29216
	v_add_f32_e32 v14, v64, v65
	v_add_f32_e32 v15, v48, v49
	v_add_f32_e32 v14, v66, v14
	v_add_f32_e32 v15, v50, v15
	v_add_f32_e32 v14, v67, v14
	v_add_f32_e32 v15, v51, v15
	v_add_f32_e32 v14, v68, v14
	v_add_f32_e32 v15, v52, v15
	v_add_f32_e32 v14, v69, v14
	v_add_f32_e32 v15, v53, v15
	v_add_f32_e32 v14, v70, v14
	v_add_f32_e32 v15, v54, v15
	v_add_f32_e32 v14, v71, v14
	v_add_f32_e32 v15, v55, v15
	v_add_f32_e32 v14, v72, v14
	v_add_f32_e32 v15, v56, v15
	v_add_f32_e32 v14, v73, v14
	v_add_f32_e32 v15, v57, v15
	v_add_f32_e32 v14, v74, v14
	v_add_f32_e32 v15, v58, v15
	v_add_f32_e32 v14, v75, v14
	v_add_f32_e32 v15, v59, v15
	v_add_f32_e32 v14, v76, v14
	v_add_f32_e32 v15, v60, v15
	v_add_f32_e32 v14, v77, v14
	v_add_f32_e32 v15, v61, v15
	v_add_f32_e32 v14, v78, v14
	v_add_f32_e32 v15, v62, v15
	v_add_f32_e32 v14, v79, v14
	v_add_f32_e32 v15, v63, v15
	v_add_f32_e32 v14, v15, v14
	v_add_f32_e32 v0, v0, v14
	s_waitcnt lgkmcnt(0)
	s_barrier
	ds_read_b128 v[132:135], v249 offset:22592
	ds_read_b128 v[136:139], v249 offset:22624
	ds_read_b128 v[140:143], v249 offset:29248
	ds_read_b128 v[144:147], v249 offset:29280
	ds_read_b128 v[166:169], v249 offset:22656
	ds_read_b128 v[170:173], v249 offset:22688
	ds_read_b128 v[174:177], v249 offset:29312
	ds_read_b128 v[178:181], v249 offset:29344
	v_mfma_f32_32x32x16_bf16 v[64:79], v[2:5], v[80:83], v[218:233]
	v_mfma_f32_32x32x16_bf16 v[48:63], v[10:13], v[80:83], v[218:233]
	v_mfma_f32_32x32x16_bf16 v[64:79], v[6:9], v[84:87], v[64:79]
	v_mfma_f32_32x32x16_bf16 v[48:63], v[128:131], v[84:87], v[48:63]
	ds_read_b128 v[128:131], v165 offset:62976
	ds_read_b128 v[10:13], v165 offset:63008
	ds_read_b128 v[2:5], v165 offset:63040
	ds_read_b128 v[6:9], v165 offset:63072
	s_waitcnt lgkmcnt(11)
	v_mfma_f32_32x32x16_bf16 v[64:79], v[132:135], v[88:91], v[64:79]
	s_waitcnt lgkmcnt(9)
	v_mfma_f32_32x32x16_bf16 v[48:63], v[140:143], v[88:91], v[48:63]
	v_mfma_f32_32x32x16_bf16 v[64:79], v[136:139], v[92:95], v[64:79]
	s_waitcnt lgkmcnt(8)
	v_mfma_f32_32x32x16_bf16 v[48:63], v[144:147], v[92:95], v[48:63]
	ds_read_b128 v[144:147], v165 offset:58368
	ds_read_b128 v[140:143], v165 offset:58400
	ds_read_b128 v[136:139], v165 offset:58432
	ds_read_b128 v[132:135], v165 offset:58464
	s_waitcnt lgkmcnt(11)
	v_mfma_f32_32x32x16_bf16 v[64:79], v[166:169], v[96:99], v[64:79]
	s_waitcnt lgkmcnt(9)
	v_mfma_f32_32x32x16_bf16 v[48:63], v[174:177], v[96:99], v[48:63]
	v_mfma_f32_32x32x16_bf16 v[64:79], v[170:173], v[100:103], v[64:79]
	s_waitcnt lgkmcnt(8)
	v_mfma_f32_32x32x16_bf16 v[48:63], v[178:181], v[100:103], v[48:63]
	s_waitcnt lgkmcnt(3)
	v_mfma_f32_32x32x16_bf16 v[32:47], v[144:147], v[188:191], v[32:47]
	v_mfma_f32_32x32x16_bf16 v[16:31], v[128:131], v[188:191], v[16:31]
	s_waitcnt lgkmcnt(2)
	v_mfma_f32_32x32x16_bf16 v[32:47], v[140:143], v[192:195], v[32:47]
	v_mfma_f32_32x32x16_bf16 v[16:31], v[10:13], v[192:195], v[16:31]
	s_waitcnt lgkmcnt(1)
	v_mfma_f32_32x32x16_bf16 v[32:47], v[136:139], v[196:199], v[32:47]
	v_mfma_f32_32x32x16_bf16 v[16:31], v[2:5], v[196:199], v[16:31]
	s_waitcnt lgkmcnt(0)
	v_mfma_f32_32x32x16_bf16 v[32:47], v[132:135], v[208:211], v[32:47]
	v_mfma_f32_32x32x16_bf16 v[16:31], v[6:9], v[208:211], v[16:31]
	s_barrier
	v_exp_f32_e32 v64, v64
	v_exp_f32_e32 v65, v65
	v_exp_f32_e32 v66, v66
	v_exp_f32_e32 v67, v67
	v_exp_f32_e32 v68, v68
	v_exp_f32_e32 v69, v69
	v_exp_f32_e32 v70, v70
	v_exp_f32_e32 v71, v71
	v_cvt_pk_bf16_f32 v188, v64, v65
	v_cvt_pk_bf16_f32 v189, v66, v67
	v_cvt_pk_bf16_f32 v190, v68, v69
	v_cvt_pk_bf16_f32 v191, v70, v71
	v_exp_f32_e32 v72, v72
	v_exp_f32_e32 v73, v73
	v_exp_f32_e32 v74, v74
	v_exp_f32_e32 v75, v75
	v_exp_f32_e32 v76, v76
	v_exp_f32_e32 v77, v77
	v_exp_f32_e32 v78, v78
	v_exp_f32_e32 v79, v79
	v_cvt_pk_bf16_f32 v192, v72, v73
	v_cvt_pk_bf16_f32 v193, v74, v75
	v_cvt_pk_bf16_f32 v194, v76, v77
	v_cvt_pk_bf16_f32 v195, v78, v79
	s_cmp_lg_u32 s13, 0
	s_cbranch_scc1 .Lppc_w2_6
	s_waitcnt vmcnt(3)
	ds_write_b128 v157, v[116:119] offset:22528
	ds_write_b128 v158, v[108:111] offset:22528
	ds_write_b128 v160, v[124:127] offset:35840
	global_load_dwordx4 v[116:119], v[238:239], off
	global_load_dwordx4 v[108:111], v[242:243], off
	global_load_dwordx4 v[124:127], v[244:245], off offset:128
	s_branch .Lppc_wj_6
.Lppc_w2_6:
	s_waitcnt vmcnt(2)
	ds_write_b128 v157, v[116:119] offset:22528
	ds_write_b128 v160, v[124:127] offset:35840
	global_load_dwordx4 v[116:119], v[238:239], off
	global_load_dwordx4 v[124:127], v[244:245], off offset:128
.Lppc_wj_6:
	v_exp_f32_e32 v48, v48
	v_exp_f32_e32 v49, v49
	v_exp_f32_e32 v50, v50
	v_exp_f32_e32 v51, v51
	v_exp_f32_e32 v52, v52
	v_exp_f32_e32 v53, v53
	v_exp_f32_e32 v54, v54
	v_exp_f32_e32 v55, v55
	v_cvt_pk_bf16_f32 v196, v48, v49
	v_cvt_pk_bf16_f32 v197, v50, v51
	v_cvt_pk_bf16_f32 v198, v52, v53
	v_cvt_pk_bf16_f32 v199, v54, v55
	v_exp_f32_e32 v56, v56
	v_exp_f32_e32 v57, v57
	v_exp_f32_e32 v58, v58
	v_exp_f32_e32 v59, v59
	v_exp_f32_e32 v60, v60
	v_exp_f32_e32 v61, v61
	v_exp_f32_e32 v62, v62
	v_exp_f32_e32 v63, v63
	v_cvt_pk_bf16_f32 v208, v56, v57
	v_cvt_pk_bf16_f32 v209, v58, v59
	v_cvt_pk_bf16_f32 v210, v60, v61
	v_cvt_pk_bf16_f32 v211, v62, v63
	ds_read_b128 v[2:5], v164
	ds_read_b128 v[6:9], v164 offset:32
	ds_read_b128 v[10:13], v164 offset:6656
	ds_read_b128 v[128:131], v164 offset:6688
	v_add_f32_e32 v14, v64, v65
	v_add_f32_e32 v15, v48, v49
	v_add_f32_e32 v14, v66, v14
	v_add_f32_e32 v15, v50, v15
	v_add_f32_e32 v14, v67, v14
	v_add_f32_e32 v15, v51, v15
	v_add_f32_e32 v14, v68, v14
	v_add_f32_e32 v15, v52, v15
	v_add_f32_e32 v14, v69, v14
	v_add_f32_e32 v15, v53, v15
	v_add_f32_e32 v14, v70, v14
	v_add_f32_e32 v15, v54, v15
	v_add_f32_e32 v14, v71, v14
	v_add_f32_e32 v15, v55, v15
	v_add_f32_e32 v14, v72, v14
	v_add_f32_e32 v15, v56, v15
	v_add_f32_e32 v14, v73, v14
	v_add_f32_e32 v15, v57, v15
	v_add_f32_e32 v14, v74, v14
	v_add_f32_e32 v15, v58, v15
	v_add_f32_e32 v14, v75, v14
	v_add_f32_e32 v15, v59, v15
	v_add_f32_e32 v14, v76, v14
	v_add_f32_e32 v15, v60, v15
	v_add_f32_e32 v14, v77, v14
	v_add_f32_e32 v15, v61, v15
	v_add_f32_e32 v14, v78, v14
	v_add_f32_e32 v15, v62, v15
	v_add_f32_e32 v14, v79, v14
	v_add_f32_e32 v15, v63, v15
	v_add_f32_e32 v14, v15, v14
	v_add_f32_e32 v0, v0, v14
	v_lshl_add_u64 v[244:245], v[244:245], 0, s[30:31]
	v_lshl_add_u64 v[236:237], v[236:237], 0, s[26:27]
	v_lshl_add_u64 v[238:239], v[238:239], 0, s[26:27]
	v_lshl_add_u64 v[240:241], v[240:241], 0, s[26:27]
	v_lshl_add_u64 v[242:243], v[242:243], 0, s[26:27]
	s_waitcnt lgkmcnt(0)
	s_barrier
	s_add_i32 s22, s22, 4
	s_cmp_ge_u32 s22, s14
	s_cbranch_scc1 .Lppc_fin
	ds_read_b128 v[132:135], v164 offset:64
	ds_read_b128 v[136:139], v164 offset:96
	ds_read_b128 v[140:143], v164 offset:6720
	ds_read_b128 v[144:147], v164 offset:6752
	ds_read_b128 v[166:169], v164 offset:128
	ds_read_b128 v[170:173], v164 offset:160
	ds_read_b128 v[174:177], v164 offset:6784
	ds_read_b128 v[178:181], v164 offset:6816
	v_mfma_f32_32x32x16_bf16 v[64:79], v[2:5], v[80:83], v[218:233]
	v_mfma_f32_32x32x16_bf16 v[48:63], v[10:13], v[80:83], v[218:233]
	v_mfma_f32_32x32x16_bf16 v[64:79], v[6:9], v[84:87], v[64:79]
	v_mfma_f32_32x32x16_bf16 v[48:63], v[128:131], v[84:87], v[48:63]
	ds_read_b128 v[128:131], v250 offset:40448
	ds_read_b128 v[10:13], v250 offset:40480
	ds_read_b128 v[2:5], v250 offset:40512
	ds_read_b128 v[6:9], v250 offset:40544
	s_waitcnt lgkmcnt(11)
	v_mfma_f32_32x32x16_bf16 v[64:79], v[132:135], v[88:91], v[64:79]
	s_waitcnt lgkmcnt(9)
	v_mfma_f32_32x32x16_bf16 v[48:63], v[140:143], v[88:91], v[48:63]
	v_mfma_f32_32x32x16_bf16 v[64:79], v[136:139], v[92:95], v[64:79]
	s_waitcnt lgkmcnt(8)
	v_mfma_f32_32x32x16_bf16 v[48:63], v[144:147], v[92:95], v[48:63]
	ds_read_b128 v[144:147], v250 offset:35840
	ds_read_b128 v[140:143], v250 offset:35872
	ds_read_b128 v[136:139], v250 offset:35904
	ds_read_b128 v[132:135], v250 offset:35936
	s_waitcnt lgkmcnt(11)
	v_mfma_f32_32x32x16_bf16 v[64:79], v[166:169], v[96:99], v[64:79]
	s_waitcnt lgkmcnt(9)
	v_mfma_f32_32x32x16_bf16 v[48:63], v[174:177], v[96:99], v[48:63]
	v_mfma_f32_32x32x16_bf16 v[64:79], v[170:173], v[100:103], v[64:79]
	s_waitcnt lgkmcnt(8)
	v_mfma_f32_32x32x16_bf16 v[48:63], v[178:181], v[100:103], v[48:63]
	s_waitcnt lgkmcnt(3)
	v_mfma_f32_32x32x16_bf16 v[32:47], v[144:147], v[188:191], v[32:47]
	v_mfma_f32_32x32x16_bf16 v[16:31], v[128:131], v[188:191], v[16:31]
	s_waitcnt lgkmcnt(2)
	v_mfma_f32_32x32x16_bf16 v[32:47], v[140:143], v[192:195], v[32:47]
	v_mfma_f32_32x32x16_bf16 v[16:31], v[10:13], v[192:195], v[16:31]
	s_waitcnt lgkmcnt(1)
	v_mfma_f32_32x32x16_bf16 v[32:47], v[136:139], v[196:199], v[32:47]
	v_mfma_f32_32x32x16_bf16 v[16:31], v[2:5], v[196:199], v[16:31]
	s_waitcnt lgkmcnt(0)
	v_mfma_f32_32x32x16_bf16 v[32:47], v[132:135], v[208:211], v[32:47]
	v_mfma_f32_32x32x16_bf16 v[16:31], v[6:9], v[208:211], v[16:31]
	s_barrier
	v_exp_f32_e32 v64, v64
	v_exp_f32_e32 v65, v65
	v_exp_f32_e32 v66, v66
	v_exp_f32_e32 v67, v67
	v_exp_f32_e32 v68, v68
	v_exp_f32_e32 v69, v69
	v_exp_f32_e32 v70, v70
	v_exp_f32_e32 v71, v71
	v_cvt_pk_bf16_f32 v188, v64, v65
	v_cvt_pk_bf16_f32 v189, v66, v67
	v_cvt_pk_bf16_f32 v190, v68, v69
	v_cvt_pk_bf16_f32 v191, v70, v71
	v_exp_f32_e32 v72, v72
	v_exp_f32_e32 v73, v73
	v_exp_f32_e32 v74, v74
	v_exp_f32_e32 v75, v75
	v_exp_f32_e32 v76, v76
	v_exp_f32_e32 v77, v77
	v_exp_f32_e32 v78, v78
	v_exp_f32_e32 v79, v79
	v_cvt_pk_bf16_f32 v192, v72, v73
	v_cvt_pk_bf16_f32 v193, v74, v75
	v_cvt_pk_bf16_f32 v194, v76, v77
	v_cvt_pk_bf16_f32 v195, v78, v79
	s_cmp_lg_u32 s13, 0
	s_cbranch_scc1 .Lppc_w2_7
	s_waitcnt vmcnt(3)
	ds_write_b128 v157, v[104:107] offset:45056
	ds_write_b128 v158, v[112:115] offset:45056
	ds_write_b128 v160, v[120:123] offset:58368
	global_load_dwordx4 v[104:107], v[236:237], off
	global_load_dwordx4 v[112:115], v[240:241], off
	global_load_dwordx4 v[120:123], v[244:245], off
	s_branch .Lppc_wj_7

.Lppc_wj_7:
	v_exp_f32_e32 v48, v48
	v_exp_f32_e32 v49, v49
	v_exp_f32_e32 v50, v50
	v_exp_f32_e32 v51, v51
	v_exp_f32_e32 v52, v52
	v_exp_f32_e32 v53, v53
	v_exp_f32_e32 v54, v54
	v_exp_f32_e32 v55, v55
	v_cvt_pk_bf16_f32 v196, v48, v49
	v_cvt_pk_bf16_f32 v197, v50, v51
	v_cvt_pk_bf16_f32 v198, v52, v53
	v_cvt_pk_bf16_f32 v199, v54, v55
	v_exp_f32_e32 v56, v56
	v_exp_f32_e32 v57, v57
	v_exp_f32_e32 v58, v58
	v_exp_f32_e32 v59, v59
	v_exp_f32_e32 v60, v60
	v_exp_f32_e32 v61, v61
	v_exp_f32_e32 v62, v62
	v_exp_f32_e32 v63, v63
	v_cvt_pk_bf16_f32 v208, v56, v57
	v_cvt_pk_bf16_f32 v209, v58, v59
	v_cvt_pk_bf16_f32 v210, v60, v61
	v_cvt_pk_bf16_f32 v211, v62, v63
	ds_read_b128 v[2:5], v164 offset:22528
	ds_read_b128 v[6:9], v164 offset:22560
	ds_read_b128 v[10:13], v164 offset:29184
	ds_read_b128 v[128:131], v164 offset:29216
	v_add_f32_e32 v14, v64, v65
	v_add_f32_e32 v15, v48, v49
	v_add_f32_e32 v14, v66, v14
	v_add_f32_e32 v15, v50, v15
	v_add_f32_e32 v14, v67, v14
	v_add_f32_e32 v15, v51, v15
	v_add_f32_e32 v14, v68, v14
	v_add_f32_e32 v15, v52, v15
	v_add_f32_e32 v14, v69, v14
	v_add_f32_e32 v15, v53, v15
	v_add_f32_e32 v14, v70, v14
	v_add_f32_e32 v15, v54, v15
	v_add_f32_e32 v14, v71, v14
	v_add_f32_e32 v15, v55, v15
	v_add_f32_e32 v14, v72, v14
	v_add_f32_e32 v15, v56, v15
	v_add_f32_e32 v14, v73, v14
	v_add_f32_e32 v15, v57, v15
	v_add_f32_e32 v14, v74, v14
	v_add_f32_e32 v15, v58, v15
	v_add_f32_e32 v14, v75, v14
	v_add_f32_e32 v15, v59, v15
	v_add_f32_e32 v14, v76, v14
	v_add_f32_e32 v15, v60, v15
	v_add_f32_e32 v14, v77, v14
	v_add_f32_e32 v15, v61, v15
	v_add_f32_e32 v14, v78, v14
	v_add_f32_e32 v15, v62, v15
	v_add_f32_e32 v14, v79, v14
	v_add_f32_e32 v15, v63, v15
	v_add_f32_e32 v14, v15, v14
	v_add_f32_e32 v0, v0, v14
	s_waitcnt lgkmcnt(0)
	s_barrier
	s_branch .Lppc_loop
.Lppc_fin:
	ds_read_b128 v[128:131], v250 offset:40448
	ds_read_b128 v[10:13], v250 offset:40480
	ds_read_b128 v[2:5], v250 offset:40512
	ds_read_b128 v[6:9], v250 offset:40544
	ds_read_b128 v[144:147], v250 offset:35840
	ds_read_b128 v[140:143], v250 offset:35872
	ds_read_b128 v[136:139], v250 offset:35904
	ds_read_b128 v[132:135], v250 offset:35936
	s_waitcnt lgkmcnt(3)
	v_mfma_f32_32x32x16_bf16 v[32:47], v[144:147], v[188:191], v[32:47]
	v_mfma_f32_32x32x16_bf16 v[16:31], v[128:131], v[188:191], v[16:31]
	s_waitcnt lgkmcnt(2)
	v_mfma_f32_32x32x16_bf16 v[32:47], v[140:143], v[192:195], v[32:47]
	v_mfma_f32_32x32x16_bf16 v[16:31], v[10:13], v[192:195], v[16:31]
	s_waitcnt lgkmcnt(1)
	v_mfma_f32_32x32x16_bf16 v[32:47], v[136:139], v[196:199], v[32:47]
	v_mfma_f32_32x32x16_bf16 v[16:31], v[2:5], v[196:199], v[16:31]
	s_waitcnt lgkmcnt(0)
	v_mfma_f32_32x32x16_bf16 v[32:47], v[132:135], v[208:211], v[32:47]
	v_mfma_f32_32x32x16_bf16 v[16:31], v[6:9], v[208:211], v[16:31]
	s_nop 15
	s_cmp_lg_u32 s13, 0
	s_cbranch_scc1 .Lppc_nolag2
	s_barrier
.Lppc_nolag2:
	s_waitcnt vmcnt(0)
	s_branch .LBB0_203
